# first grid barrier: the 16 per-XCD counter loads of the one-time discovery loop issued together with a single wait (was load, wait, add per counter)
# baseline (speedup 1.0000x reference)
.LBB0_26:
	v_readlane_b32 s4, v248, 44
	v_readlane_b32 s5, v248, 45
	s_mov_b64 s[22:23], -1
	s_mov_b64 s[28:29], -1
	s_nop 2
	global_load_dword v1, v0, s[4:5] sc1
	v_readlane_b32 s4, v248, 46
	v_readlane_b32 s5, v248, 47
	s_nop 4
	global_load_dword v2, v0, s[4:5] sc1
	v_readlane_b32 s4, v248, 48
	v_readlane_b32 s5, v248, 49
	s_nop 1
	s_nop 2
	global_load_dword v3, v0, s[4:5] sc1
	v_readlane_b32 s4, v248, 50
	v_readlane_b32 s5, v248, 51
	s_nop 1
	s_nop 2
	global_load_dword v4, v0, s[4:5] sc1
	v_readlane_b32 s4, v248, 52
	v_readlane_b32 s5, v248, 53
	s_nop 1
	s_nop 2
	global_load_dword v5, v0, s[4:5] sc1
	v_readlane_b32 s4, v248, 54
	v_readlane_b32 s5, v248, 55
	s_nop 1
	s_nop 2
	global_load_dword v6, v0, s[4:5] sc1
	v_readlane_b32 s4, v248, 56
	v_readlane_b32 s5, v248, 57
	s_nop 1
	s_nop 2
	global_load_dword v7, v0, s[4:5] sc1
	v_readlane_b32 s4, v248, 58
	v_readlane_b32 s5, v248, 59
	s_nop 1
	s_nop 2
	global_load_dword v8, v0, s[4:5] sc1
	v_readlane_b32 s4, v248, 60
	v_readlane_b32 s5, v248, 61
	s_nop 1
	s_nop 2
	global_load_dword v9, v0, s[4:5] sc1
	v_readlane_b32 s4, v248, 62
	v_readlane_b32 s5, v248, 63
	s_nop 1
	s_nop 2
	global_load_dword v10, v0, s[4:5] sc1
	v_readlane_b32 s4, v247, 0
	v_readlane_b32 s5, v247, 1
	s_nop 1
	s_nop 2
	global_load_dword v11, v0, s[4:5] sc1
	v_readlane_b32 s4, v247, 2
	v_readlane_b32 s5, v247, 3
	s_nop 1
	s_nop 2
	global_load_dword v12, v0, s[4:5] sc1
	v_readlane_b32 s4, v247, 4
	v_readlane_b32 s5, v247, 5
	s_nop 1
	s_nop 2
	global_load_dword v13, v0, s[4:5] sc1
	v_readlane_b32 s4, v247, 6
	v_readlane_b32 s5, v247, 7
	s_nop 1
	s_nop 2
	global_load_dword v14, v0, s[4:5] sc1
	v_readlane_b32 s4, v247, 8
	v_readlane_b32 s5, v247, 9
	s_nop 1
	s_nop 2
	global_load_dword v15, v0, s[4:5] sc1
	v_readlane_b32 s4, v247, 10
	v_readlane_b32 s5, v247, 11
	s_nop 1
	s_nop 2
	global_load_dword v16, v0, s[4:5] sc1
	s_nop 1
	s_waitcnt vmcnt(0)
	v_add_u32_e32 v17, v2, v1
	v_add_u32_e32 v17, v17, v3
	v_add_u32_e32 v17, v17, v4
	v_add_u32_e32 v17, v17, v5
	v_add_u32_e32 v17, v17, v6
	v_add_u32_e32 v17, v17, v7
	v_add_u32_e32 v17, v17, v8
	v_add_u32_e32 v17, v17, v9
	v_add_u32_e32 v17, v17, v10
	v_add_u32_e32 v17, v17, v11
	v_add_u32_e32 v17, v17, v12
	v_add_u32_e32 v17, v17, v13
	v_add_u32_e32 v17, v17, v14
	v_add_u32_e32 v17, v17, v15
	v_add_u32_e32 v17, v17, v16
	v_cmp_eq_u32_e32 vcc, s2, v17
	s_cbranch_vccnz .LBB0_25
	s_and_b32 s22, s24, 0xff
	s_cmp_eq_u32 s22, 0
	s_mov_b64 s[22:23], -1
	s_mov_b64 s[34:35], -1
	s_sleep 1
	s_cbranch_scc0 .LBB0_30
	v_readlane_b32 s4, v248, 42
	v_readlane_b32 s5, v248, 43
	s_nop 4
	global_load_dword v17, v0, s[4:5] sc1
	s_waitcnt vmcnt(0)
	v_cmp_eq_u32_e32 vcc, 0, v17
	s_cbranch_vccnz .LBB0_32
	s_mov_b64 s[34:35], 0
